# w2 transposes moved into mixer idle time, split at item 0x4000
# speedup vs baseline: 1.0032x; 1.0007x over previous
; __device__ __forceinline__ void phase_wconv_rest(const Params& p, LAS unsigned char* lds, int gw, int NGW) {
;     ...
;     for (int it = gw; it < NITEMS; it += NGW) {
;         int r = it;
;         if (r < I_A) { transpose_item<false, false>(p.w_a, WA, D_MODEL, (bf16*)(ws + WS_WAT), 0, scr, r, lane); continue; } r -= I_A;
;         if (r < I_A) { transpose_item<false, false>(p.w_b, WA, D_MODEL, (bf16*)(ws + WS_WBT), 0, scr, r, lane); continue; } r -= I_A;
;         if (r < I_O) { transpose_item<false, false>(p.w_o, D_MODEL, D_MODEL, (bf16*)(ws + WS_WOT), 0, scr, r, lane); continue; } r -= I_O;
;         if (r < I_1) { transpose_item<false, true>(p.w1, D_MODEL, FFN, (bf16*)(ws + WS_W13T), 0, scr, r, lane, sh2, b2); continue; } r -= I_1;
;         if (r < I_1) { transpose_item<false, true>(p.w3, D_MODEL, FFN, (bf16*)(ws + WS_W13T), 128, scr, r, lane, sh2, b2); continue; } r -= I_1;
;         transpose_item<false, false>(p.w2, FFN, D_MODEL, (bf16*)(ws + WS_W2T), 0, scr, r, lane);
; __global__ void __launch_bounds__(NTHREADS, 2) mega_fwd(Params p_in) {
;     ...
;       const int nfree = nb - CTX_UNITS;
;       if (nfree >= 64) { if (bx >= CTX_UNITS) phase_wconv_rest(p, lds, (bx - CTX_UNITS) * 8 + wave_id, nfree * 8); }
.LBB0_240:
	s_cmpk_lt_i32 s2, 0x50
	s_cbranch_scc1 .LBB0_268
	s_lshl_b32 s4, s2, 3
	s_add_i32 s4, s4, s3
	s_add_i32 s20, s4, 0xfffffd80
	s_cmpk_gt_i32 s20, 0x3fff
	v_mbcnt_lo_u32_b32 v0, -1, 0
	v_mbcnt_hi_u32_b32 v0, -1, v0
	s_cbranch_scc1 .LBB0_268
	s_add_i32 s21, s46, 0xfffffd80
	s_waitcnt lgkmcnt(0)
	s_add_u32 s6, s22, 0x106000
	s_addc_u32 s7, s23, 0
	s_add_u32 s16, s22, 0x18000
	s_addc_u32 s17, s23, 0
	s_lshl_b32 s3, s3, 14
	v_ashrrev_i32_e32 v34, 5, v0
	v_lshlrev_b32_e32 v1, 2, v0
	s_movk_i32 s4, 0x84
	s_add_i32 s3, s3, 0
	v_and_b32_e32 v22, 0x7c, v1
	v_mul_lo_u32 v1, v34, s4
	v_add3_u32 v26, s3, v22, v1
	v_lshlrev_b32_e32 v1, 3, v0
	v_and_b32_e32 v1, 56, v1
	v_ashrrev_i32_e32 v35, 3, v0
	v_lshlrev_b32_e32 v12, 1, v1
	v_mov_b32_e32 v13, 0
	v_mul_u32_u24_e32 v4, 0x84, v1
	v_lshl_add_u64 v[10:11], s[22:23], 0, v[12:13]
	v_lshlrev_b32_e32 v1, 2, v35
	s_mov_b64 s[22:23], 0x142000
	v_add3_u32 v27, s3, v4, v1
	v_lshl_add_u64 v[4:5], v[10:11], 0, s[22:23]
	s_mov_b64 s[22:23], 0x4b42000
	v_lshl_add_u64 v[6:7], v[10:11], 0, s[22:23]
	s_mov_b64 s[22:23], 0x4742000
	s_mov_b64 s[4:5], 0x2d42000
	v_ashrrev_i32_e32 v1, 31, v0
	v_lshl_add_u64 v[8:9], v[10:11], 0, s[22:23]
	s_mov_b64 s[22:23], 0x4342000
	v_mov_b32_e32 v23, v13
	s_mov_b32 s19, 0
	v_lshl_add_u64 v[2:3], v[10:11], 0, s[4:5]
	v_add_u32_e32 v36, 8, v35
	v_add_u32_e32 v37, 16, v35
	v_add_u32_e32 v38, 24, v35
	v_cmp_gt_i32_e64 s[4:5], 32, v0
	v_lshl_add_u64 v[10:11], v[10:11], 0, s[22:23]
	v_lshl_add_u64 v[12:13], s[42:43], 0, v[22:23]
	v_lshl_add_u64 v[14:15], s[40:41], 0, v[22:23]
	v_lshl_add_u64 v[16:17], s[14:15], 0, v[22:23]
	v_lshl_add_u64 v[18:19], s[12:13], 0, v[22:23]
	v_lshl_add_u64 v[20:21], s[10:11], 0, v[22:23]
	v_lshl_add_u64 v[22:23], s[8:9], 0, v[22:23]
	v_lshl_add_u64 v[24:25], v[0:1], 2, s[16:17]
	s_lshl_b32 s3, s20, 5
	s_lshl_b32 s12, s21, 5
	s_mov_b32 s13, 0xc000
	s_mov_b32 s14, 0x18000
	s_mov_b32 s15, 0x24000
	s_movk_i32 s22, 0x2c00
	s_movk_i32 s23, 0x5800
	v_add_u32_e32 v39, 0x4000, v26
	v_add_u32_e32 v40, 0x4400, v26
	v_add_u32_e32 v41, 0x4800, v26
	v_add_u32_e32 v42, 0x4c00, v26
	v_add_u32_e32 v43, 0x5000, v26
	v_add_u32_e32 v44, 0x5400, v26
	v_add_u32_e32 v45, 0x5800, v26
	v_add_u32_e32 v46, 0x5c00, v26
	v_add_u32_e32 v47, 0x4000, v27
	s_branch .LBB0_244
.LBB0_243:
	s_add_i32 s20, s20, s21
	s_add_i32 s3, s3, s12
	s_cmpk_gt_i32 s20, 0x3fff
	s_cbranch_scc1 .LBB0_268

; __device__ __forceinline__ int lane_id() { int l; asm volatile("v_mbcnt_lo_u32_b32 %0, -1, 0\n\tv_mbcnt_hi_u32_b32 %0, -1, %0" : "=v"(l)); return l; }
; #define LOAD_P() Params p; { const __attribute__((address_space(4))) Params* q_ = (const __attribute__((address_space(4))) Params*)__builtin_amdgcn_kernarg_segment_ptr(); asm volatile("" : "+s"(q_)); \
;     p = *q_; p.wave_id = wave_id; } unsigned char* ws = p.ws; (void)ws
; __device__ __forceinline__ void phase_wconv_rest(const Params& p, LAS unsigned char* lds, int gw, int NGW) {
;     ...
;     for (int it = gw; it < NITEMS; it += NGW) {
;         int r = it;
;         if (r < I_A) { transpose_item<false, false>(p.w_a, WA, D_MODEL, (bf16*)(ws + WS_WAT), 0, scr, r, lane); continue; } r -= I_A;
;         if (r < I_A) { transpose_item<false, false>(p.w_b, WA, D_MODEL, (bf16*)(ws + WS_WBT), 0, scr, r, lane); continue; } r -= I_A;
;         if (r < I_O) { transpose_item<false, false>(p.w_o, D_MODEL, D_MODEL, (bf16*)(ws + WS_WOT), 0, scr, r, lane); continue; } r -= I_O;
;         if (r < I_1) { transpose_item<false, true>(p.w1, D_MODEL, FFN, (bf16*)(ws + WS_W13T), 0, scr, r, lane, sh2, b2); continue; } r -= I_1;
;         if (r < I_1) { transpose_item<false, true>(p.w3, D_MODEL, FFN, (bf16*)(ws + WS_W13T), 128, scr, r, lane, sh2, b2); continue; } r -= I_1;
;         transpose_item<false, false>(p.w2, FFN, D_MODEL, (bf16*)(ws + WS_W2T), 0, scr, r, lane);
; __global__ void __launch_bounds__(NTHREADS, 2) mega_fwd(Params p_in) {
;     ...
;     { LOAD_P();
;       if (bx < 2 * BATCH * NHEAD) {
;         if (wave_id == 0 && lane_id() == 0) { unsigned* pc = (unsigned*)(ws + WS_PREPCTR); while (__hip_atomic_load(pc, __ATOMIC_RELAXED, __HIP_MEMORY_SCOPE_AGENT) < (unsigned)nb) __builtin_amdgcn_s_sleep(2); }
;         asm volatile("" ::: "memory"); __syncthreads();
;         hgrn_scan(p, lds, bx); }
;       __syncthreads();
;       phase_attn(p, lds); }
.LBB0_505:
	s_cmpk_lt_i32 s2, 0x40
	s_cbranch_scc1 .Lw2_skip
	v_writelane_b32 v250, s3, 40
	v_writelane_b32 v250, s12, 41
	v_writelane_b32 v250, s18, 42
	v_writelane_b32 v250, s19, 43
	v_writelane_b32 v250, s20, 44
	v_writelane_b32 v250, s21, 45
	v_writelane_b32 v250, s22, 46
	v_writelane_b32 v250, s23, 47
	v_writelane_b32 v250, s24, 48
	v_writelane_b32 v250, s25, 49
	v_writelane_b32 v250, s26, 50
	v_writelane_b32 v250, s27, 51
	s_lshr_b32 s3, s76, 6
	s_load_dwordx8 s[8:15], s[0:1], 0x70
	s_load_dwordx2 s[40:41], s[0:1], 0x90
	s_load_dwordx2 s[42:43], s[0:1], 0xa8
	s_load_dwordx2 s[22:23], s[0:1], 0xb8
	s_waitcnt vmcnt(0) lgkmcnt(0)
	s_barrier
	s_lshl_b32 s4, s2, 3
	s_add_i32 s4, s4, s3
	s_add_i32 s20, s4, 0x3e00
	s_cmpk_gt_i32 s20, 0x51ff
	v_mbcnt_lo_u32_b32 v0, -1, 0
	v_mbcnt_hi_u32_b32 v0, -1, v0
	s_cbranch_scc1 .Lw2_done
	s_movk_i32 s21, 0x600
	s_waitcnt lgkmcnt(0)
	s_add_u32 s6, s22, 0x106000
	s_addc_u32 s7, s23, 0
	s_add_u32 s16, s22, 0x18000
	s_addc_u32 s17, s23, 0
	s_lshl_b32 s3, s3, 14
	v_ashrrev_i32_e32 v34, 5, v0
	v_lshlrev_b32_e32 v1, 2, v0
	s_movk_i32 s4, 0x84
	s_add_i32 s3, s3, 0
	v_and_b32_e32 v22, 0x7c, v1
	v_mul_lo_u32 v1, v34, s4
	v_add3_u32 v26, s3, v22, v1
	v_lshlrev_b32_e32 v1, 3, v0
	v_and_b32_e32 v1, 56, v1
	v_ashrrev_i32_e32 v35, 3, v0
	v_lshlrev_b32_e32 v12, 1, v1
	v_mov_b32_e32 v13, 0
	v_mul_u32_u24_e32 v4, 0x84, v1
	v_lshl_add_u64 v[10:11], s[22:23], 0, v[12:13]
	v_lshlrev_b32_e32 v1, 2, v35
	s_mov_b64 s[22:23], 0x142000
	v_add3_u32 v27, s3, v4, v1
	v_lshl_add_u64 v[4:5], v[10:11], 0, s[22:23]
	s_mov_b64 s[22:23], 0x4b42000
	v_lshl_add_u64 v[6:7], v[10:11], 0, s[22:23]
	s_mov_b64 s[22:23], 0x4742000
	s_mov_b64 s[4:5], 0x2d42000
	v_ashrrev_i32_e32 v1, 31, v0
	v_lshl_add_u64 v[8:9], v[10:11], 0, s[22:23]
	s_mov_b64 s[22:23], 0x4342000
	v_mov_b32_e32 v23, v13
	s_mov_b32 s19, 0
	v_lshl_add_u64 v[2:3], v[10:11], 0, s[4:5]
	v_add_u32_e32 v36, 8, v35
	v_add_u32_e32 v37, 16, v35
	v_add_u32_e32 v38, 24, v35
	v_cmp_gt_i32_e64 s[4:5], 32, v0
	v_lshl_add_u64 v[10:11], v[10:11], 0, s[22:23]
	v_lshl_add_u64 v[12:13], s[42:43], 0, v[22:23]
	v_lshl_add_u64 v[14:15], s[40:41], 0, v[22:23]
	v_lshl_add_u64 v[16:17], s[14:15], 0, v[22:23]
	v_lshl_add_u64 v[18:19], s[12:13], 0, v[22:23]
	v_lshl_add_u64 v[20:21], s[10:11], 0, v[22:23]
	v_lshl_add_u64 v[22:23], s[8:9], 0, v[22:23]
	v_lshl_add_u64 v[24:25], v[0:1], 2, s[16:17]
	s_lshl_b32 s3, s20, 5
	s_lshl_b32 s12, s21, 5
	s_mov_b32 s13, 0xc000
	s_mov_b32 s14, 0x18000
	s_mov_b32 s15, 0x24000
	s_movk_i32 s22, 0x2c00
	s_movk_i32 s23, 0x5800
	v_add_u32_e32 v39, 0x4000, v26
	v_add_u32_e32 v40, 0x4400, v26
	v_add_u32_e32 v41, 0x4800, v26
	v_add_u32_e32 v42, 0x4c00, v26
	v_add_u32_e32 v43, 0x5000, v26
	v_add_u32_e32 v44, 0x5400, v26
	v_add_u32_e32 v45, 0x5800, v26
	v_add_u32_e32 v46, 0x5c00, v26
	v_add_u32_e32 v47, 0x4000, v27
	s_branch .Lw2c_244
